# hand-written GLU arm for E_G1 pn<4 tiles added on top of the E_FFN1 arm
# baseline (speedup 1.0000x reference)
; #define PG8_STAGE(bufoff, gbase, voff) do { _Pragma("unroll") for (int _i = 0; _i < 2; ++_i) \
;         __builtin_amdgcn_global_load_lds((const unsigned*)((const char*)(gbase) + (voff)[_i]), (LAS unsigned*)(lds + (bufoff) + ldsw + _i * 8192), 16, 0, 0); } while (0)
; #define PG8_LDA(dst, b, h) do { _Pragma("unroll") for (int m = 0; m < 4; ++m) _Pragma("unroll") for (int k = 0; k < 2; ++k) dst[m][k] = *(const LAS bf16x8*)(lds + PG8_SA(b, h) + aoff + m * 2048 + k * 1024); } while (0)
; #define PG8_LDB(dst, b, h) do { _Pragma("unroll") for (int n = 0; n < 2; ++n) _Pragma("unroll") for (int k = 0; k < 2; ++k) dst[n][k] = *(const LAS bf16x8*)(lds + PG8_SB(b, h) + boff + n * 2048 + k * 1024); } while (0)
; #define PG8_MMA(ai, bj, At, Bt) do { __builtin_amdgcn_s_setprio(1); _Pragma("unroll") for (int m = 0; m < 4; ++m) _Pragma("unroll") for (int n = 0; n < 2; ++n) _Pragma("unroll") for (int k = 0; k < 2; ++k) \
;         acc[ai][bj][m][n] = __builtin_amdgcn_mfma_f32_16x16x32_bf16(Bt[n][k], At[m][k], acc[ai][bj][m][n], 0, 0, 0); __builtin_amdgcn_s_setprio(0); } while (0)
; #define PG8_WAIT_L(n) asm volatile("s_waitcnt lgkmcnt(" #n ")" ::: "memory")
; #define PG8_BAR __builtin_amdgcn_s_barrier()
; #define PG8_SCHED __builtin_amdgcn_sched_barrier(0)
; __device__ __forceinline__ void gemm_phase(LAS unsigned char* lds, CParams& p, const Job& jb) {
;     ...
;             PG8_LDB(B0, 0, 0); PG8_SCHED; PG8_LDA(At, 0, 0); PG8_STAGE(PG8_SA(1, 1), a1 + hstepA, voffA);
;             PG8_WAIT_L(8); PG8_BAR; PG8_WAIT_L(0); PG8_MMA(0, 0, At, B0); PG8_BAR; PG8_SCHED;
;             PG8_LDB(B1, 0, 1); PG8_STAGE(PG8_SB(0, 0), b2, voffB);
;             PG8_BAR; PG8_WAIT_L(0); PG8_MMA(0, 1, At, B1); PG8_BAR;
;             PG8_LDA(At, 0, 1); PG8_STAGE(PG8_SA(0, 0), a2, voffA);
;             PG8_BAR; PG8_WAIT_L(0); PG8_MMA(1, 0, At, B0); PG8_BAR; PG8_SCHED;
.LBB0_631:
	s_add_i32 s1, s1, 2
	s_add_u32 s12, s24, s10
	s_addc_u32 s13, s25, s11
	s_add_u32 s12, s12, 0x100
	s_addc_u32 s13, s13, 0
	s_add_u32 s14, s97, s10
	s_addc_u32 s15, s2, s11
	s_add_i32 s16, 0, 0x10000
	v_add_u32_e32 v144, s16, v213
	ds_read_b128 v[132:135], v144
	ds_read_b128 v[136:139], v144 offset:1024
	ds_read_b128 v[140:143], v144 offset:2048
	ds_read_b128 v[144:147], v144 offset:3072
	s_cmp_eq_u32 s85, s10
	s_cselect_b32 s13, s5, s13
	s_cselect_b32 s12, s4, s12
	s_cselect_b32 s15, s87, s15
	s_cselect_b32 s14, s86, s14
	v_lshl_add_u64 v[216:217], v[128:129], 0, s[10:11]
	s_add_i32 m0, s65, 0xc000
	ds_read_b128 v[148:151], v214
	ds_read_b128 v[152:155], v214 offset:1024
	ds_read_b128 v[156:159], v214 offset:2048
	ds_read_b128 v[172:175], v214 offset:3072
	ds_read_b128 v[176:179], v214 offset:4096
	ds_read_b128 v[180:183], v214 offset:5120
	ds_read_b128 v[184:187], v214 offset:6144
	ds_read_b128 v[188:191], v214 offset:7168
	global_load_lds_dwordx4 v[216:217], off
	v_lshl_add_u64 v[216:217], v[130:131], 0, s[10:11]
	s_add_i32 m0, s65, 0xe000
	s_nop 0
	global_load_lds_dwordx4 v[216:217], off
	s_waitcnt lgkmcnt(8)
	s_barrier
	s_waitcnt lgkmcnt(0)
	s_setprio 1
	s_waitcnt lgkmcnt(0)
	v_mfma_f32_16x16x32_bf16 v[124:127], v[132:135], v[148:151], v[124:127]
	v_mfma_f32_16x16x32_bf16 v[120:123], v[140:143], v[148:151], v[120:123]
	v_mfma_f32_16x16x32_bf16 v[116:119], v[132:135], v[156:159], v[116:119]
	v_mfma_f32_16x16x32_bf16 v[112:115], v[140:143], v[156:159], v[112:115]
	v_mfma_f32_16x16x32_bf16 v[108:111], v[132:135], v[176:179], v[108:111]
	v_mfma_f32_16x16x32_bf16 v[104:107], v[140:143], v[176:179], v[104:107]
	v_mfma_f32_16x16x32_bf16 v[100:103], v[132:135], v[184:187], v[100:103]
	v_mfma_f32_16x16x32_bf16 v[96:99], v[140:143], v[184:187], v[96:99]
	v_mfma_f32_16x16x32_bf16 v[124:127], v[136:139], v[152:155], v[124:127]
	v_mfma_f32_16x16x32_bf16 v[120:123], v[144:147], v[152:155], v[120:123]
	v_mfma_f32_16x16x32_bf16 v[116:119], v[136:139], v[172:175], v[116:119]
	v_mfma_f32_16x16x32_bf16 v[112:115], v[144:147], v[172:175], v[112:115]
	v_mfma_f32_16x16x32_bf16 v[108:111], v[136:139], v[180:183], v[108:111]
	v_mfma_f32_16x16x32_bf16 v[104:107], v[144:147], v[180:183], v[104:107]
	v_mfma_f32_16x16x32_bf16 v[100:103], v[136:139], v[188:191], v[100:103]
	v_mfma_f32_16x16x32_bf16 v[96:99], v[144:147], v[188:191], v[96:99]
	s_setprio 0
	s_barrier
	s_add_i32 s17, 0, 0x14000
	s_add_i32 s16, s16, s64
	v_add_u32_e32 v215, s17, v213
	v_lshl_add_u64 v[232:233], s[14:15], 0, v[160:161]
	s_mov_b32 m0, s16
	ds_read_b128 v[216:219], v215
	ds_read_b128 v[220:223], v215 offset:1024
	ds_read_b128 v[224:227], v215 offset:2048
	ds_read_b128 v[228:231], v215 offset:3072
	global_load_lds_dwordx4 v[232:233], off
	v_lshl_add_u64 v[234:235], s[14:15], 0, v[166:167]
	s_add_i32 m0, s16, 0x2000
	s_nop 0
	global_load_lds_dwordx4 v[234:235], off
	s_barrier
	s_waitcnt lgkmcnt(0)
	s_setprio 1
	s_waitcnt lgkmcnt(0)
	v_mfma_f32_16x16x32_bf16 v[92:95], v[216:219], v[148:151], v[92:95]
	v_mfma_f32_16x16x32_bf16 v[88:91], v[224:227], v[148:151], v[88:91]
	v_mfma_f32_16x16x32_bf16 v[84:87], v[216:219], v[156:159], v[84:87]
	v_mfma_f32_16x16x32_bf16 v[80:83], v[224:227], v[156:159], v[80:83]
	v_mfma_f32_16x16x32_bf16 v[76:79], v[216:219], v[176:179], v[76:79]
	v_mfma_f32_16x16x32_bf16 v[72:75], v[224:227], v[176:179], v[72:75]
	v_mfma_f32_16x16x32_bf16 v[68:71], v[216:219], v[184:187], v[68:71]
	v_mfma_f32_16x16x32_bf16 v[64:67], v[224:227], v[184:187], v[64:67]
	v_mfma_f32_16x16x32_bf16 v[92:95], v[220:223], v[152:155], v[92:95]
	v_mfma_f32_16x16x32_bf16 v[88:91], v[228:231], v[152:155], v[88:91]
	v_mfma_f32_16x16x32_bf16 v[84:87], v[220:223], v[172:175], v[84:87]
	v_mfma_f32_16x16x32_bf16 v[80:83], v[228:231], v[172:175], v[80:83]
	v_mfma_f32_16x16x32_bf16 v[76:79], v[220:223], v[180:183], v[76:79]
	v_mfma_f32_16x16x32_bf16 v[72:75], v[228:231], v[180:183], v[72:75]
	v_mfma_f32_16x16x32_bf16 v[68:71], v[220:223], v[188:191], v[68:71]
	v_mfma_f32_16x16x32_bf16 v[64:67], v[228:231], v[188:191], v[64:67]
	s_setprio 0
	s_mov_b32 m0, s65
	v_lshl_add_u64 v[236:237], s[12:13], 0, v[162:163]
	s_barrier
	ds_read_b128 v[148:151], v214 offset:16384
	ds_read_b128 v[152:155], v214 offset:17408
	ds_read_b128 v[156:159], v214 offset:18432
	ds_read_b128 v[172:175], v214 offset:19456
	ds_read_b128 v[176:179], v214 offset:20480
	ds_read_b128 v[180:183], v214 offset:21504
	ds_read_b128 v[184:187], v214 offset:22528
	ds_read_b128 v[188:191], v214 offset:23552
	global_load_lds_dwordx4 v[236:237], off
	v_lshl_add_u64 v[238:239], s[12:13], 0, v[164:165]
	s_mov_b32 m0, s66
	s_nop 0
	global_load_lds_dwordx4 v[238:239], off
	s_barrier
	s_waitcnt lgkmcnt(0)
	s_setprio 1
	s_waitcnt lgkmcnt(0)
	v_mfma_f32_16x16x32_bf16 v[60:63], v[132:135], v[148:151], v[60:63]
	v_mfma_f32_16x16x32_bf16 v[56:59], v[140:143], v[148:151], v[56:59]
	v_mfma_f32_16x16x32_bf16 v[52:55], v[132:135], v[156:159], v[52:55]
	v_mfma_f32_16x16x32_bf16 v[48:51], v[140:143], v[156:159], v[48:51]
	v_mfma_f32_16x16x32_bf16 v[44:47], v[132:135], v[176:179], v[44:47]
	v_mfma_f32_16x16x32_bf16 v[40:43], v[140:143], v[176:179], v[40:43]
	v_mfma_f32_16x16x32_bf16 v[36:39], v[132:135], v[184:187], v[36:39]
	v_mfma_f32_16x16x32_bf16 v[32:35], v[140:143], v[184:187], v[32:35]
	v_mfma_f32_16x16x32_bf16 v[60:63], v[136:139], v[152:155], v[60:63]
	v_mfma_f32_16x16x32_bf16 v[56:59], v[144:147], v[152:155], v[56:59]
	v_mfma_f32_16x16x32_bf16 v[52:55], v[136:139], v[172:175], v[52:55]
	v_mfma_f32_16x16x32_bf16 v[48:51], v[144:147], v[172:175], v[48:51]
	v_mfma_f32_16x16x32_bf16 v[44:47], v[136:139], v[180:183], v[44:47]
	v_mfma_f32_16x16x32_bf16 v[40:43], v[144:147], v[180:183], v[40:43]
	v_mfma_f32_16x16x32_bf16 v[36:39], v[136:139], v[188:191], v[36:39]
	v_mfma_f32_16x16x32_bf16 v[32:35], v[144:147], v[188:191], v[32:35]
	s_setprio 0
	s_barrier
; #define PG8_STAGE(bufoff, gbase, voff) do { _Pragma("unroll") for (int _i = 0; _i < 2; ++_i) \
;         __builtin_amdgcn_global_load_lds((const unsigned*)((const char*)(gbase) + (voff)[_i]), (LAS unsigned*)(lds + (bufoff) + ldsw + _i * 8192), 16, 0, 0); } while (0)
; #define PG8_LDA(dst, b, h) do { _Pragma("unroll") for (int m = 0; m < 4; ++m) _Pragma("unroll") for (int k = 0; k < 2; ++k) dst[m][k] = *(const LAS bf16x8*)(lds + PG8_SA(b, h) + aoff + m * 2048 + k * 1024); } while (0)
; #define PG8_LDB(dst, b, h) do { _Pragma("unroll") for (int n = 0; n < 2; ++n) _Pragma("unroll") for (int k = 0; k < 2; ++k) dst[n][k] = *(const LAS bf16x8*)(lds + PG8_SB(b, h) + boff + n * 2048 + k * 1024); } while (0)
; #define PG8_MMA(ai, bj, At, Bt) do { __builtin_amdgcn_s_setprio(1); _Pragma("unroll") for (int m = 0; m < 4; ++m) _Pragma("unroll") for (int n = 0; n < 2; ++n) _Pragma("unroll") for (int k = 0; k < 2; ++k) \
;         acc[ai][bj][m][n] = __builtin_amdgcn_mfma_f32_16x16x32_bf16(Bt[n][k], At[m][k], acc[ai][bj][m][n], 0, 0, 0); __builtin_amdgcn_s_setprio(0); } while (0)
; #define PG8_WAIT_V(n) asm volatile("s_waitcnt vmcnt(" #n ")" ::: "memory")
; #define PG8_WAIT_L(n) asm volatile("s_waitcnt lgkmcnt(" #n ")" ::: "memory")
; #define PG8_BAR __builtin_amdgcn_s_barrier()
; #define PG8_SCHED __builtin_amdgcn_sched_barrier(0)
; __device__ __forceinline__ void gemm_phase(LAS unsigned char* lds, CParams& p, const Job& jb) {
;     ...
;             PG8_STAGE(PG8_SB(0, 1), b2 + hstepB, voffB);
;             PG8_WAIT_V(6); PG8_BAR; PG8_MMA(1, 1, At, B1); PG8_BAR;
;             PG8_LDB(B0, 1, 0); PG8_SCHED; PG8_LDA(At, 1, 0); PG8_STAGE(PG8_SA(0, 1), a2 + hstepA, voffA);
;             PG8_WAIT_L(8); PG8_BAR; PG8_WAIT_L(0); PG8_MMA(0, 0, At, B0); PG8_BAR; PG8_SCHED;
;             PG8_LDB(B1, 1, 1); PG8_STAGE(PG8_SB(1, 0), b3, voffB);
;             PG8_BAR; PG8_WAIT_L(0); PG8_MMA(0, 1, At, B1); PG8_BAR;
;             PG8_LDA(At, 1, 1); PG8_STAGE(PG8_SA(1, 0), a3, voffA);
;             PG8_BAR; PG8_WAIT_L(0); PG8_MMA(1, 0, At, B0); PG8_BAR; PG8_SCHED;
	s_add_u32 s14, s14, s76
	s_addc_u32 s15, s15, s77
	s_add_i32 s16, s17, s64
	v_lshl_add_u64 v[240:241], s[14:15], 0, v[160:161]
	s_mov_b32 m0, s16
	v_lshl_add_u64 v[242:243], s[14:15], 0, v[166:167]
	global_load_lds_dwordx4 v[240:241], off
	s_add_i32 m0, s16, 0x2000
	s_nop 0
	global_load_lds_dwordx4 v[242:243], off
	s_waitcnt vmcnt(6)
	s_barrier
	s_setprio 1
	v_mfma_f32_16x16x32_bf16 v[28:31], v[216:219], v[148:151], v[28:31]
	v_mfma_f32_16x16x32_bf16 v[24:27], v[224:227], v[148:151], v[24:27]
	v_mfma_f32_16x16x32_bf16 v[20:23], v[216:219], v[156:159], v[20:23]
	v_mfma_f32_16x16x32_bf16 v[16:19], v[224:227], v[156:159], v[16:19]
	v_mfma_f32_16x16x32_bf16 v[12:15], v[216:219], v[176:179], v[12:15]
	v_mfma_f32_16x16x32_bf16 v[8:11], v[224:227], v[176:179], v[8:11]
	v_mfma_f32_16x16x32_bf16 v[4:7], v[216:219], v[184:187], v[4:7]
	v_mfma_f32_16x16x32_bf16 v[0:3], v[224:227], v[184:187], v[0:3]
	v_mfma_f32_16x16x32_bf16 v[28:31], v[220:223], v[152:155], v[28:31]
	v_mfma_f32_16x16x32_bf16 v[24:27], v[228:231], v[152:155], v[24:27]
	v_mfma_f32_16x16x32_bf16 v[20:23], v[220:223], v[172:175], v[20:23]
	v_mfma_f32_16x16x32_bf16 v[16:19], v[228:231], v[172:175], v[16:19]
	v_mfma_f32_16x16x32_bf16 v[12:15], v[220:223], v[180:183], v[12:15]
	v_mfma_f32_16x16x32_bf16 v[8:11], v[228:231], v[180:183], v[8:11]
	v_mfma_f32_16x16x32_bf16 v[4:7], v[220:223], v[188:191], v[4:7]
	v_mfma_f32_16x16x32_bf16 v[0:3], v[228:231], v[188:191], v[0:3]
	s_setprio 0
	s_add_i32 s14, 0, 0x18000
	v_add_u32_e32 v144, s14, v213
	s_barrier
	ds_read_b128 v[132:135], v144
	ds_read_b128 v[136:139], v144 offset:1024
	ds_read_b128 v[140:143], v144 offset:2048
	ds_read_b128 v[144:147], v144 offset:3072
	s_add_u32 s12, s12, s74
	s_addc_u32 s13, s13, s75
	s_mov_b32 m0, s67
	v_lshl_add_u64 v[216:217], s[12:13], 0, v[162:163]
	ds_read_b128 v[148:151], v214 offset:32768
	ds_read_b128 v[152:155], v214 offset:33792
	ds_read_b128 v[156:159], v214 offset:34816
	ds_read_b128 v[172:175], v214 offset:35840
	ds_read_b128 v[176:179], v214 offset:36864
	ds_read_b128 v[180:183], v214 offset:37888
	ds_read_b128 v[184:187], v214 offset:38912
	ds_read_b128 v[188:191], v214 offset:39936
	global_load_lds_dwordx4 v[216:217], off
	v_lshl_add_u64 v[216:217], s[12:13], 0, v[164:165]
	s_mov_b32 m0, s94
	s_nop 0
	global_load_lds_dwordx4 v[216:217], off
	s_waitcnt lgkmcnt(8)
	s_barrier
	s_waitcnt lgkmcnt(0)
	s_setprio 1
	s_waitcnt lgkmcnt(0)
	v_mfma_f32_16x16x32_bf16 v[124:127], v[132:135], v[148:151], v[124:127]
	v_mfma_f32_16x16x32_bf16 v[120:123], v[140:143], v[148:151], v[120:123]
	v_mfma_f32_16x16x32_bf16 v[116:119], v[132:135], v[156:159], v[116:119]
	v_mfma_f32_16x16x32_bf16 v[112:115], v[140:143], v[156:159], v[112:115]
	v_mfma_f32_16x16x32_bf16 v[108:111], v[132:135], v[176:179], v[108:111]
	v_mfma_f32_16x16x32_bf16 v[104:107], v[140:143], v[176:179], v[104:107]
	v_mfma_f32_16x16x32_bf16 v[100:103], v[132:135], v[184:187], v[100:103]
	v_mfma_f32_16x16x32_bf16 v[96:99], v[140:143], v[184:187], v[96:99]
	v_mfma_f32_16x16x32_bf16 v[124:127], v[136:139], v[152:155], v[124:127]
	v_mfma_f32_16x16x32_bf16 v[120:123], v[144:147], v[152:155], v[120:123]
	v_mfma_f32_16x16x32_bf16 v[116:119], v[136:139], v[172:175], v[116:119]
	v_mfma_f32_16x16x32_bf16 v[112:115], v[144:147], v[172:175], v[112:115]
	v_mfma_f32_16x16x32_bf16 v[108:111], v[136:139], v[180:183], v[108:111]
	v_mfma_f32_16x16x32_bf16 v[104:107], v[144:147], v[180:183], v[104:107]
	v_mfma_f32_16x16x32_bf16 v[100:103], v[136:139], v[188:191], v[100:103]
	v_mfma_f32_16x16x32_bf16 v[96:99], v[144:147], v[188:191], v[96:99]
	s_setprio 0
	s_barrier
	s_add_i32 s12, 0, 0x1c000
	s_add_i32 s13, s14, s64
	v_add_u32_e32 v215, s12, v213
	v_lshl_add_u64 v[232:233], v[232:233], 0, s[90:91]
	s_mov_b32 m0, s13
	ds_read_b128 v[216:219], v215
	ds_read_b128 v[220:223], v215 offset:1024
	ds_read_b128 v[224:227], v215 offset:2048
	ds_read_b128 v[228:231], v215 offset:3072
	global_load_lds_dwordx4 v[232:233], off
	v_lshl_add_u64 v[232:233], v[234:235], 0, s[90:91]
	s_add_i32 m0, s13, 0x2000
	s_nop 0
	global_load_lds_dwordx4 v[232:233], off
	s_barrier
	s_waitcnt lgkmcnt(0)
	s_setprio 1
	s_waitcnt lgkmcnt(0)
	v_mfma_f32_16x16x32_bf16 v[92:95], v[216:219], v[148:151], v[92:95]
	v_mfma_f32_16x16x32_bf16 v[88:91], v[224:227], v[148:151], v[88:91]
	v_mfma_f32_16x16x32_bf16 v[84:87], v[216:219], v[156:159], v[84:87]
	v_mfma_f32_16x16x32_bf16 v[80:83], v[224:227], v[156:159], v[80:83]
	v_mfma_f32_16x16x32_bf16 v[76:79], v[216:219], v[176:179], v[76:79]
	v_mfma_f32_16x16x32_bf16 v[72:75], v[224:227], v[176:179], v[72:75]
	v_mfma_f32_16x16x32_bf16 v[68:71], v[216:219], v[184:187], v[68:71]
	v_mfma_f32_16x16x32_bf16 v[64:67], v[224:227], v[184:187], v[64:67]
	v_mfma_f32_16x16x32_bf16 v[92:95], v[220:223], v[152:155], v[92:95]
	v_mfma_f32_16x16x32_bf16 v[88:91], v[228:231], v[152:155], v[88:91]
	v_mfma_f32_16x16x32_bf16 v[84:87], v[220:223], v[172:175], v[84:87]
	v_mfma_f32_16x16x32_bf16 v[80:83], v[228:231], v[172:175], v[80:83]
	v_mfma_f32_16x16x32_bf16 v[76:79], v[220:223], v[180:183], v[76:79]
	v_mfma_f32_16x16x32_bf16 v[72:75], v[228:231], v[180:183], v[72:75]
	v_mfma_f32_16x16x32_bf16 v[68:71], v[220:223], v[188:191], v[68:71]
	v_mfma_f32_16x16x32_bf16 v[64:67], v[228:231], v[188:191], v[64:67]
	s_setprio 0
	s_mov_b32 m0, s33
	v_lshl_add_u64 v[232:233], v[236:237], 0, s[90:91]
	s_barrier
	ds_read_b128 v[148:151], v214 offset:49152
	ds_read_b128 v[152:155], v214 offset:50176
	ds_read_b128 v[156:159], v214 offset:51200
	ds_read_b128 v[172:175], v214 offset:52224
	ds_read_b128 v[176:179], v214 offset:53248
	ds_read_b128 v[180:183], v214 offset:54272
	ds_read_b128 v[184:187], v214 offset:55296
	ds_read_b128 v[188:191], v214 offset:56320
	global_load_lds_dwordx4 v[232:233], off
	v_lshl_add_u64 v[232:233], v[238:239], 0, s[90:91]
	s_mov_b32 m0, s60
	s_nop 0
	global_load_lds_dwordx4 v[232:233], off
	s_barrier
; __device__ __forceinline__ u32x4 pack8(f32x4 a, f32x4 b) { u32x4 w; w.x = pk2(a[0], a[1]); w.y = pk2(a[2], a[3]); w.z = pk2(b[0], b[1]); w.w = pk2(b[2], b[3]); return w; }
; __device__ __forceinline__ f32x4 sigm4(f32x4 v) { return (f32x4){sigm(v[0]), sigm(v[1]), sigm(v[2]), sigm(v[3])}; }
; #define FOR_ROWS _Pragma("unroll") for (int ai = 0; ai < 2; ++ai) _Pragma("unroll") for (int m = 0; m < 4; ++m)
; #define PG8_STAGE(bufoff, gbase, voff) do { _Pragma("unroll") for (int _i = 0; _i < 2; ++_i) \
;         __builtin_amdgcn_global_load_lds((const unsigned*)((const char*)(gbase) + (voff)[_i]), (LAS unsigned*)(lds + (bufoff) + ldsw + _i * 8192), 16, 0, 0); } while (0)
; #define PG8_MMA(ai, bj, At, Bt) do { __builtin_amdgcn_s_setprio(1); _Pragma("unroll") for (int m = 0; m < 4; ++m) _Pragma("unroll") for (int n = 0; n < 2; ++n) _Pragma("unroll") for (int k = 0; k < 2; ++k) \
;         acc[ai][bj][m][n] = __builtin_amdgcn_mfma_f32_16x16x32_bf16(Bt[n][k], At[m][k], acc[ai][bj][m][n], 0, 0, 0); __builtin_amdgcn_s_setprio(0); } while (0)
; #define PG8_WAIT_V(n) asm volatile("s_waitcnt vmcnt(" #n ")" ::: "memory")
; #define PG8_WAIT_L(n) asm volatile("s_waitcnt lgkmcnt(" #n ")" ::: "memory")
; #define PG8_BAR __builtin_amdgcn_s_barrier()
; #define PG8_SCHED __builtin_amdgcn_sched_barrier(0)
; __device__ __forceinline__ void epilogue(const int kind, CParams& p, const f32x4 (&acc)[2][2][4][2], const Unit& u, const int wr, const int wc, const int fr_in, const int fq_in) {
;     ...
;     case E_G1: {
;         if (u.pn < 4) {
;             FOR_ROWS { ROWDEF
;                 const f32x4 a0 = acc[ai][0][m][0], a1 = acc[ai][0][m][1], b0 = sigm4(acc[ai][1][m][0]), b1 = sigm4(acc[ai][1][m][1]);
;                 *(u32x4*)(p.u + row * DCV + u.pn * 128 + cw) = pack8(a0 * b0, a1 * b1); }
; __device__ __forceinline__ void gemm_phase(LAS unsigned char* lds, CParams& p, const Job& jb) {
;     ...
;             PG8_BAR; PG8_WAIT_L(0); PG8_MMA(1, 0, At, B0); PG8_BAR; PG8_SCHED;
;             PG8_STAGE(PG8_SB(1, 1), b3 + hstepB, voffB);
;             PG8_WAIT_V(6); PG8_BAR; PG8_MMA(1, 1, At, B1); PG8_BAR;
;         }
;         epilogue(cur.kind, p, acc, cur, wr, wc, fr, fq);
	s_waitcnt lgkmcnt(0)
	s_setprio 1
	s_waitcnt lgkmcnt(0)
	v_mfma_f32_16x16x32_bf16 v[60:63], v[132:135], v[148:151], v[60:63]
	v_mfma_f32_16x16x32_bf16 v[56:59], v[140:143], v[148:151], v[56:59]
	v_mfma_f32_16x16x32_bf16 v[52:55], v[132:135], v[156:159], v[52:55]
	v_mfma_f32_16x16x32_bf16 v[48:51], v[140:143], v[156:159], v[48:51]
	v_mfma_f32_16x16x32_bf16 v[44:47], v[132:135], v[176:179], v[44:47]
	v_mfma_f32_16x16x32_bf16 v[40:43], v[140:143], v[176:179], v[40:43]
	v_mfma_f32_16x16x32_bf16 v[36:39], v[132:135], v[184:187], v[36:39]
	v_mfma_f32_16x16x32_bf16 v[32:35], v[140:143], v[184:187], v[32:35]
	v_mfma_f32_16x16x32_bf16 v[60:63], v[136:139], v[152:155], v[60:63]
	v_mfma_f32_16x16x32_bf16 v[56:59], v[144:147], v[152:155], v[56:59]
	v_mfma_f32_16x16x32_bf16 v[52:55], v[136:139], v[172:175], v[52:55]
	v_mfma_f32_16x16x32_bf16 v[48:51], v[144:147], v[172:175], v[48:51]
	v_mfma_f32_16x16x32_bf16 v[44:47], v[136:139], v[180:183], v[44:47]
	v_mfma_f32_16x16x32_bf16 v[40:43], v[144:147], v[180:183], v[40:43]
	v_mfma_f32_16x16x32_bf16 v[36:39], v[136:139], v[188:191], v[36:39]
	v_mfma_f32_16x16x32_bf16 v[32:35], v[144:147], v[188:191], v[32:35]
	s_setprio 0
	s_barrier
	s_add_i32 s12, s12, s64
	v_lshl_add_u64 v[132:133], v[240:241], 0, s[90:91]
	s_mov_b32 m0, s12
	s_nop 0
	global_load_lds_dwordx4 v[132:133], off
	v_lshl_add_u64 v[132:133], v[242:243], 0, s[90:91]
	s_add_i32 m0, s12, 0x2000
	s_nop 0
	global_load_lds_dwordx4 v[132:133], off
	s_waitcnt vmcnt(6)
	s_barrier
	s_setprio 1
	v_mfma_f32_16x16x32_bf16 v[28:31], v[216:219], v[148:151], v[28:31]
	v_mfma_f32_16x16x32_bf16 v[24:27], v[224:227], v[148:151], v[24:27]
	v_mfma_f32_16x16x32_bf16 v[20:23], v[216:219], v[156:159], v[20:23]
	v_mfma_f32_16x16x32_bf16 v[16:19], v[224:227], v[156:159], v[16:19]
	v_mfma_f32_16x16x32_bf16 v[12:15], v[216:219], v[176:179], v[12:15]
	v_mfma_f32_16x16x32_bf16 v[8:11], v[224:227], v[176:179], v[8:11]
	v_mfma_f32_16x16x32_bf16 v[4:7], v[216:219], v[184:187], v[4:7]
	v_mfma_f32_16x16x32_bf16 v[0:3], v[224:227], v[184:187], v[0:3]
	v_mfma_f32_16x16x32_bf16 v[28:31], v[220:223], v[152:155], v[28:31]
	v_mfma_f32_16x16x32_bf16 v[24:27], v[228:231], v[152:155], v[24:27]
	v_mfma_f32_16x16x32_bf16 v[20:23], v[220:223], v[172:175], v[20:23]
	v_mfma_f32_16x16x32_bf16 v[16:19], v[228:231], v[172:175], v[16:19]
	v_mfma_f32_16x16x32_bf16 v[12:15], v[220:223], v[180:183], v[12:15]
	v_mfma_f32_16x16x32_bf16 v[8:11], v[228:231], v[180:183], v[8:11]
	v_mfma_f32_16x16x32_bf16 v[4:7], v[220:223], v[188:191], v[4:7]
	v_mfma_f32_16x16x32_bf16 v[0:3], v[228:231], v[188:191], v[0:3]
	s_setprio 0
	s_add_u32 s10, s10, 0x100
	s_addc_u32 s11, s11, 0
	s_cmp_ge_u32 s1, s84
	s_barrier
	s_cbranch_scc0 .LBB0_631
	v_mov_b32_e32 v215, v211
	v_mov_b32_e32 v216, v212
	s_cmp_eq_u32 s3, 13
	s_cbranch_scc1 .Lmy_down
	s_cmp_eq_u32 s3, 12
	s_cbranch_scc1 .Lmy_ffn1
	s_cmp_lg_u32 s3, 0
	s_cbranch_scc1 .Lnot_glu
	s_cmp_lt_i32 s92, 4
	s_cbranch_scc1 .Lmy_glu
.Lnot_glu:
	s_cmp_lt_i32 s3, 7
	v_lshl_add_u32 v172, v216, 3, s31
	s_mov_b64 s[10:11], -1
	s_cbranch_scc1 .LBB0_849
	s_cmp_lt_i32 s3, 11
	s_cbranch_scc1 .LBB0_639
	s_cmp_gt_i32 s3, 12
	s_cbranch_scc0 .LBB0_640
	s_cmp_gt_i32 s3, 13
	s_mov_b64 s[26:27], -1
	s_cbranch_scc0 .LBB0_641
	s_cmp_eq_u32 s3, 14
	s_cbranch_scc0 .LBB0_638
	v_add_u32_e32 v128, s0, v215
	s_ashr_i32 s79, s78, 31
	v_ashrrev_i32_e32 v129, 31, v128
	v_lshl_add_u64 v[130:131], v[128:129], 0, s[78:79]
	s_lshl_b32 s10, s92, 8
	v_lshlrev_b64 v[130:131], 12, v[130:131]
	s_ashr_i32 s11, s10, 31
	v_ashrrev_i32_e32 v173, 31, v172
	v_lshl_add_u64 v[130:131], s[82:83], 0, v[130:131]
	s_lshl_b64 s[10:11], s[10:11], 2
	v_lshl_add_u64 v[130:131], v[130:131], 0, s[10:11]
	v_lshlrev_b64 v[132:133], 2, v[172:173]
	v_lshl_add_u64 v[130:131], v[130:131], 0, v[132:133]
	global_atomic_add_f32 v[130:131], v124, off
	global_atomic_add_f32 v[130:131], v120, off offset:16
	global_atomic_add_f32 v[130:131], v125, off offset:4
	global_atomic_add_f32 v[130:131], v121, off offset:20
	global_atomic_add_f32 v[130:131], v126, off offset:8
	global_atomic_add_f32 v[130:131], v122, off offset:24
	global_atomic_add_f32 v[130:131], v127, off offset:12
	global_atomic_add_f32 v[130:131], v123, off offset:28
	global_atomic_add_f32 v[130:131], v92, off offset:512
	global_atomic_add_f32 v[130:131], v88, off offset:528
	global_atomic_add_f32 v[130:131], v93, off offset:516
	global_atomic_add_f32 v[130:131], v89, off offset:532
	global_atomic_add_f32 v[130:131], v94, off offset:520
	global_atomic_add_f32 v[130:131], v90, off offset:536
	global_atomic_add_f32 v[130:131], v95, off offset:524
	global_atomic_add_f32 v[130:131], v91, off offset:540
	v_add_u32_e32 v130, 16, v128
	v_ashrrev_i32_e32 v131, 31, v130
	v_lshl_add_u64 v[130:131], v[130:131], 0, s[78:79]
	v_lshlrev_b64 v[130:131], 12, v[130:131]
	v_lshl_add_u64 v[130:131], s[82:83], 0, v[130:131]
	v_lshl_add_u64 v[130:131], v[130:131], 0, s[10:11]
	v_lshl_add_u64 v[130:131], v[130:131], 0, v[132:133]
	global_atomic_add_f32 v[130:131], v116, off
	global_atomic_add_f32 v[130:131], v112, off offset:16
	global_atomic_add_f32 v[130:131], v117, off offset:4
	global_atomic_add_f32 v[130:131], v113, off offset:20
	global_atomic_add_f32 v[130:131], v118, off offset:8
	global_atomic_add_f32 v[130:131], v114, off offset:24
	global_atomic_add_f32 v[130:131], v119, off offset:12
	global_atomic_add_f32 v[130:131], v115, off offset:28
	global_atomic_add_f32 v[130:131], v84, off offset:512
	global_atomic_add_f32 v[130:131], v80, off offset:528
	global_atomic_add_f32 v[130:131], v85, off offset:516
	global_atomic_add_f32 v[130:131], v81, off offset:532
	global_atomic_add_f32 v[130:131], v86, off offset:520
; #define FOR_ROWS _Pragma("unroll") for (int ai = 0; ai < 2; ++ai) _Pragma("unroll") for (int m = 0; m < 4; ++m)
; __device__ __forceinline__ void epilogue(const int kind, CParams& p, const f32x4 (&acc)[2][2][4][2], const Unit& u, const int wr, const int wc, const int fr_in, const int fq_in) {
;     ...
;         FOR_ROWS { ROWDEF
; #pragma unroll
;             for (int bj = 0; bj < 2; ++bj) { float* hp = p.out + row * 1024 + u.pn * 256 + bj * 128 + cw;
; #pragma unroll
;                 for (int j = 0; j < 4; ++j) { unsafeAtomicAdd(hp + j, acc[ai][bj][m][0][j]); unsafeAtomicAdd(hp + 4 + j, acc[ai][bj][m][1][j]); } } }
	global_atomic_add_f32 v[130:131], v82, off offset:536
	global_atomic_add_f32 v[130:131], v87, off offset:524
	global_atomic_add_f32 v[130:131], v83, off offset:540
	v_add_u32_e32 v130, 32, v128
	v_ashrrev_i32_e32 v131, 31, v130
	v_lshl_add_u64 v[130:131], v[130:131], 0, s[78:79]
	v_lshlrev_b64 v[130:131], 12, v[130:131]
	v_lshl_add_u64 v[130:131], s[82:83], 0, v[130:131]
	v_lshl_add_u64 v[130:131], v[130:131], 0, s[10:11]
	v_lshl_add_u64 v[130:131], v[130:131], 0, v[132:133]
	global_atomic_add_f32 v[130:131], v108, off
	global_atomic_add_f32 v[130:131], v104, off offset:16
	global_atomic_add_f32 v[130:131], v109, off offset:4
	global_atomic_add_f32 v[130:131], v105, off offset:20
	global_atomic_add_f32 v[130:131], v110, off offset:8
	global_atomic_add_f32 v[130:131], v106, off offset:24
	global_atomic_add_f32 v[130:131], v111, off offset:12
	global_atomic_add_f32 v[130:131], v107, off offset:28
	global_atomic_add_f32 v[130:131], v76, off offset:512
	global_atomic_add_f32 v[130:131], v72, off offset:528
	global_atomic_add_f32 v[130:131], v77, off offset:516
	global_atomic_add_f32 v[130:131], v73, off offset:532
	global_atomic_add_f32 v[130:131], v78, off offset:520
	global_atomic_add_f32 v[130:131], v74, off offset:536
	global_atomic_add_f32 v[130:131], v79, off offset:524
	global_atomic_add_f32 v[130:131], v75, off offset:540
	v_add_u32_e32 v130, 48, v128
	v_ashrrev_i32_e32 v131, 31, v130
	v_lshl_add_u64 v[130:131], v[130:131], 0, s[78:79]
	v_lshlrev_b64 v[130:131], 12, v[130:131]
	v_lshl_add_u64 v[130:131], s[82:83], 0, v[130:131]
	v_lshl_add_u64 v[130:131], v[130:131], 0, s[10:11]
	v_lshl_add_u64 v[130:131], v[130:131], 0, v[132:133]
	global_atomic_add_f32 v[130:131], v100, off
	global_atomic_add_f32 v[130:131], v96, off offset:16
	global_atomic_add_f32 v[130:131], v101, off offset:4
	global_atomic_add_f32 v[130:131], v97, off offset:20
	global_atomic_add_f32 v[130:131], v102, off offset:8
	global_atomic_add_f32 v[130:131], v98, off offset:24
	global_atomic_add_f32 v[130:131], v103, off offset:12
	global_atomic_add_f32 v[130:131], v99, off offset:28
	global_atomic_add_f32 v[130:131], v68, off offset:512
	global_atomic_add_f32 v[130:131], v64, off offset:528
	global_atomic_add_f32 v[130:131], v69, off offset:516
	global_atomic_add_f32 v[130:131], v65, off offset:532
	global_atomic_add_f32 v[130:131], v70, off offset:520
	global_atomic_add_f32 v[130:131], v66, off offset:536
	global_atomic_add_f32 v[130:131], v71, off offset:524
	global_atomic_add_f32 v[130:131], v67, off offset:540
	v_add_u32_e32 v130, 0x80, v128
	v_ashrrev_i32_e32 v131, 31, v130
	v_lshl_add_u64 v[130:131], v[130:131], 0, s[78:79]
	v_lshlrev_b64 v[130:131], 12, v[130:131]
	v_lshl_add_u64 v[130:131], s[82:83], 0, v[130:131]
	v_lshl_add_u64 v[130:131], v[130:131], 0, s[10:11]
	v_lshl_add_u64 v[130:131], v[130:131], 0, v[132:133]
	global_atomic_add_f32 v[130:131], v60, off
	global_atomic_add_f32 v[130:131], v56, off offset:16
	global_atomic_add_f32 v[130:131], v61, off offset:4
	global_atomic_add_f32 v[130:131], v57, off offset:20
	global_atomic_add_f32 v[130:131], v62, off offset:8
	global_atomic_add_f32 v[130:131], v58, off offset:24
	global_atomic_add_f32 v[130:131], v63, off offset:12
	global_atomic_add_f32 v[130:131], v59, off offset:28
	global_atomic_add_f32 v[130:131], v28, off offset:512
	global_atomic_add_f32 v[130:131], v24, off offset:528
	global_atomic_add_f32 v[130:131], v29, off offset:516
	global_atomic_add_f32 v[130:131], v25, off offset:532
	global_atomic_add_f32 v[130:131], v30, off offset:520
	global_atomic_add_f32 v[130:131], v26, off offset:536
; #define FOR_ROWS _Pragma("unroll") for (int ai = 0; ai < 2; ++ai) _Pragma("unroll") for (int m = 0; m < 4; ++m)
; __device__ __forceinline__ void epilogue(const int kind, CParams& p, const f32x4 (&acc)[2][2][4][2], const Unit& u, const int wr, const int wc, const int fr_in, const int fq_in) {
;     ...
;         FOR_ROWS { ROWDEF
; #pragma unroll
;             for (int bj = 0; bj < 2; ++bj) { float* hp = p.out + row * 1024 + u.pn * 256 + bj * 128 + cw;
; #pragma unroll
;                 for (int j = 0; j < 4; ++j) { unsafeAtomicAdd(hp + j, acc[ai][bj][m][0][j]); unsafeAtomicAdd(hp + 4 + j, acc[ai][bj][m][1][j]); } } }
	global_atomic_add_f32 v[130:131], v31, off offset:524
	global_atomic_add_f32 v[130:131], v27, off offset:540
	v_add_u32_e32 v130, 0x90, v128
	v_ashrrev_i32_e32 v131, 31, v130
	v_lshl_add_u64 v[130:131], v[130:131], 0, s[78:79]
	v_lshlrev_b64 v[130:131], 12, v[130:131]
	v_lshl_add_u64 v[130:131], s[82:83], 0, v[130:131]
	v_lshl_add_u64 v[130:131], v[130:131], 0, s[10:11]
	v_lshl_add_u64 v[130:131], v[130:131], 0, v[132:133]
	global_atomic_add_f32 v[130:131], v52, off
	global_atomic_add_f32 v[130:131], v48, off offset:16
	global_atomic_add_f32 v[130:131], v53, off offset:4
	global_atomic_add_f32 v[130:131], v49, off offset:20
	global_atomic_add_f32 v[130:131], v54, off offset:8
	global_atomic_add_f32 v[130:131], v50, off offset:24
	global_atomic_add_f32 v[130:131], v55, off offset:12
	global_atomic_add_f32 v[130:131], v51, off offset:28
	global_atomic_add_f32 v[130:131], v20, off offset:512
	global_atomic_add_f32 v[130:131], v16, off offset:528
	global_atomic_add_f32 v[130:131], v21, off offset:516
	global_atomic_add_f32 v[130:131], v17, off offset:532
	global_atomic_add_f32 v[130:131], v22, off offset:520
	global_atomic_add_f32 v[130:131], v18, off offset:536
	global_atomic_add_f32 v[130:131], v23, off offset:524
	global_atomic_add_f32 v[130:131], v19, off offset:540
	v_add_u32_e32 v130, 0xa0, v128
	v_ashrrev_i32_e32 v131, 31, v130
	v_add_u32_e32 v128, 0xb0, v128
	v_lshl_add_u64 v[130:131], v[130:131], 0, s[78:79]
	v_ashrrev_i32_e32 v129, 31, v128
	v_lshlrev_b64 v[130:131], 12, v[130:131]
	v_lshl_add_u64 v[128:129], v[128:129], 0, s[78:79]
	v_lshl_add_u64 v[130:131], s[82:83], 0, v[130:131]
	v_lshlrev_b64 v[128:129], 12, v[128:129]
	v_lshl_add_u64 v[130:131], v[130:131], 0, s[10:11]
	v_lshl_add_u64 v[128:129], s[82:83], 0, v[128:129]
	v_lshl_add_u64 v[130:131], v[130:131], 0, v[132:133]
	v_lshl_add_u64 v[128:129], v[128:129], 0, s[10:11]
	global_atomic_add_f32 v[130:131], v44, off
	global_atomic_add_f32 v[130:131], v40, off offset:16
	global_atomic_add_f32 v[130:131], v45, off offset:4
	global_atomic_add_f32 v[130:131], v41, off offset:20
	global_atomic_add_f32 v[130:131], v46, off offset:8
	global_atomic_add_f32 v[130:131], v42, off offset:24
	global_atomic_add_f32 v[130:131], v47, off offset:12
	global_atomic_add_f32 v[130:131], v43, off offset:28
	global_atomic_add_f32 v[130:131], v12, off offset:512
	global_atomic_add_f32 v[130:131], v8, off offset:528
	global_atomic_add_f32 v[130:131], v13, off offset:516
	global_atomic_add_f32 v[130:131], v9, off offset:532
	global_atomic_add_f32 v[130:131], v14, off offset:520
	global_atomic_add_f32 v[130:131], v10, off offset:536
	global_atomic_add_f32 v[130:131], v15, off offset:524
	global_atomic_add_f32 v[130:131], v11, off offset:540
	v_lshl_add_u64 v[128:129], v[128:129], 0, v[132:133]
	global_atomic_add_f32 v[128:129], v36, off
	global_atomic_add_f32 v[128:129], v32, off offset:16
	global_atomic_add_f32 v[128:129], v37, off offset:4
	global_atomic_add_f32 v[128:129], v33, off offset:20
	global_atomic_add_f32 v[128:129], v38, off offset:8
	global_atomic_add_f32 v[128:129], v34, off offset:24
	global_atomic_add_f32 v[128:129], v39, off offset:12
	global_atomic_add_f32 v[128:129], v35, off offset:28
	global_atomic_add_f32 v[128:129], v4, off offset:512
	global_atomic_add_f32 v[128:129], v0, off offset:528
	global_atomic_add_f32 v[128:129], v5, off offset:516
	global_atomic_add_f32 v[128:129], v1, off offset:532
	global_atomic_add_f32 v[128:129], v6, off offset:520
	global_atomic_add_f32 v[128:129], v2, off offset:536
	global_atomic_add_f32 v[128:129], v7, off offset:524
	global_atomic_add_f32 v[128:129], v3, off offset:540

; __device__ __forceinline__ u32x4 pack8(f32x4 a, f32x4 b) { u32x4 w; w.x = pk2(a[0], a[1]); w.y = pk2(a[2], a[3]); w.z = pk2(b[0], b[1]); w.w = pk2(b[2], b[3]); return w; }
; __device__ __forceinline__ f32x4 sigm4(f32x4 v) { return (f32x4){sigm(v[0]), sigm(v[1]), sigm(v[2]), sigm(v[3])}; }
; #define FOR_ROWS _Pragma("unroll") for (int ai = 0; ai < 2; ++ai) _Pragma("unroll") for (int m = 0; m < 4; ++m)
; __device__ __forceinline__ void epilogue(const int kind, CParams& p, const f32x4 (&acc)[2][2][4][2], const Unit& u, const int wr, const int wc, const int fr_in, const int fq_in) {
;     ...
;     case E_G1: {
;         if (u.pn < 4) {
;             FOR_ROWS { ROWDEF
;                 const f32x4 a0 = acc[ai][0][m][0], a1 = acc[ai][0][m][1], b0 = sigm4(acc[ai][1][m][0]), b1 = sigm4(acc[ai][1][m][1]);
;                 *(u32x4*)(p.u + row * DCV + u.pn * 128 + cw) = pack8(a0 * b0, a1 * b1); }
.Lmy_glu:
	v_readlane_b32 s12, v245, 55
	v_readlane_b32 s13, v245, 56
	v_lshl_add_u32 v220, v216, 3, s31
	v_add_u32_e32 v224, s0, v215
	v_add_u32_e32 v224, s78, v224
	s_load_dwordx2 s[14:15], s[12:13], 0x230
	s_lshl_b32 s1, s92, 8
	v_lshlrev_b32_e32 v217, 10, v224
	v_lshl_add_u32 v217, v220, 1, v217
	v_add_u32_e32 v217, s1, v217
	v_mov_b32_e32 v242, 0xbfb8aa3b
	v_mov_b32_e32 v243, 0xbfb8aa3b
	s_waitcnt lgkmcnt(0)
	v_mov_b32_e32 v218, v217
	v_pk_mul_f32 v[128:129], v[92:93], v[242:243]
	v_pk_mul_f32 v[130:131], v[94:95], v[242:243]
	v_pk_mul_f32 v[132:133], v[88:89], v[242:243]
	v_pk_mul_f32 v[134:135], v[90:91], v[242:243]
	v_exp_f32_e32 v128, v128
	v_exp_f32_e32 v129, v129
	v_exp_f32_e32 v130, v130
	v_exp_f32_e32 v131, v131
	v_exp_f32_e32 v132, v132
	v_exp_f32_e32 v133, v133
	v_exp_f32_e32 v134, v134
	v_exp_f32_e32 v135, v135
	v_pk_add_f32 v[128:129], v[128:129], 1.0 op_sel_hi:[1,0]
	v_pk_add_f32 v[130:131], v[130:131], 1.0 op_sel_hi:[1,0]
	v_pk_add_f32 v[132:133], v[132:133], 1.0 op_sel_hi:[1,0]
	v_pk_add_f32 v[134:135], v[134:135], 1.0 op_sel_hi:[1,0]
	v_rcp_f32_e32 v128, v128
	v_rcp_f32_e32 v129, v129
	v_rcp_f32_e32 v130, v130
	v_rcp_f32_e32 v131, v131
	v_rcp_f32_e32 v132, v132
	v_rcp_f32_e32 v133, v133
	v_rcp_f32_e32 v134, v134
	v_rcp_f32_e32 v135, v135
	v_pk_mul_f32 v[124:125], v[124:125], v[128:129]
	v_pk_mul_f32 v[126:127], v[126:127], v[130:131]
	v_pk_mul_f32 v[120:121], v[120:121], v[132:133]
	v_pk_mul_f32 v[122:123], v[122:123], v[134:135]
	v_cvt_pk_bf16_f32 v136, v124, v125
	v_cvt_pk_bf16_f32 v137, v126, v127
	v_cvt_pk_bf16_f32 v138, v120, v121
	v_cvt_pk_bf16_f32 v139, v122, v123
	global_store_dwordx4 v218, v[136:139], s[14:15]
	v_add_u32_e32 v219, 0x4000, v217
	v_pk_mul_f32 v[140:141], v[84:85], v[242:243]
	v_pk_mul_f32 v[142:143], v[86:87], v[242:243]
	v_pk_mul_f32 v[144:145], v[80:81], v[242:243]
	v_pk_mul_f32 v[146:147], v[82:83], v[242:243]
	v_exp_f32_e32 v140, v140
	v_exp_f32_e32 v141, v141
	v_exp_f32_e32 v142, v142
	v_exp_f32_e32 v143, v143
	v_exp_f32_e32 v144, v144
	v_exp_f32_e32 v145, v145
	v_exp_f32_e32 v146, v146
	v_exp_f32_e32 v147, v147
	v_pk_add_f32 v[140:141], v[140:141], 1.0 op_sel_hi:[1,0]
	v_pk_add_f32 v[142:143], v[142:143], 1.0 op_sel_hi:[1,0]
	v_pk_add_f32 v[144:145], v[144:145], 1.0 op_sel_hi:[1,0]
	v_pk_add_f32 v[146:147], v[146:147], 1.0 op_sel_hi:[1,0]
	v_rcp_f32_e32 v140, v140
	v_rcp_f32_e32 v141, v141
	v_rcp_f32_e32 v142, v142
	v_rcp_f32_e32 v143, v143
	v_rcp_f32_e32 v144, v144
	v_rcp_f32_e32 v145, v145
	v_rcp_f32_e32 v146, v146
	v_rcp_f32_e32 v147, v147
	v_pk_mul_f32 v[116:117], v[116:117], v[140:141]
	v_pk_mul_f32 v[118:119], v[118:119], v[142:143]
	v_pk_mul_f32 v[112:113], v[112:113], v[144:145]
	v_pk_mul_f32 v[114:115], v[114:115], v[146:147]
	v_cvt_pk_bf16_f32 v148, v116, v117
	v_cvt_pk_bf16_f32 v149, v118, v119
	v_cvt_pk_bf16_f32 v150, v112, v113
	v_cvt_pk_bf16_f32 v151, v114, v115
	global_store_dwordx4 v219, v[148:151], s[14:15]
	v_add_u32_e32 v218, 0x8000, v217
	v_pk_mul_f32 v[128:129], v[76:77], v[242:243]
	v_pk_mul_f32 v[130:131], v[78:79], v[242:243]
	v_pk_mul_f32 v[132:133], v[72:73], v[242:243]
	v_pk_mul_f32 v[134:135], v[74:75], v[242:243]
	v_exp_f32_e32 v128, v128
	v_exp_f32_e32 v129, v129
	v_exp_f32_e32 v130, v130
	v_exp_f32_e32 v131, v131
	v_exp_f32_e32 v132, v132
	v_exp_f32_e32 v133, v133
	v_exp_f32_e32 v134, v134
	v_exp_f32_e32 v135, v135
	v_pk_add_f32 v[128:129], v[128:129], 1.0 op_sel_hi:[1,0]
	v_pk_add_f32 v[130:131], v[130:131], 1.0 op_sel_hi:[1,0]
	v_pk_add_f32 v[132:133], v[132:133], 1.0 op_sel_hi:[1,0]
	v_pk_add_f32 v[134:135], v[134:135], 1.0 op_sel_hi:[1,0]
	v_rcp_f32_e32 v128, v128
	v_rcp_f32_e32 v129, v129
	v_rcp_f32_e32 v130, v130
	v_rcp_f32_e32 v131, v131
	v_rcp_f32_e32 v132, v132
	v_rcp_f32_e32 v133, v133
	v_rcp_f32_e32 v134, v134
	v_rcp_f32_e32 v135, v135
	v_pk_mul_f32 v[108:109], v[108:109], v[128:129]
	v_pk_mul_f32 v[110:111], v[110:111], v[130:131]
	v_pk_mul_f32 v[104:105], v[104:105], v[132:133]
	v_pk_mul_f32 v[106:107], v[106:107], v[134:135]
	v_cvt_pk_bf16_f32 v136, v108, v109
	v_cvt_pk_bf16_f32 v137, v110, v111
	v_cvt_pk_bf16_f32 v138, v104, v105
	v_cvt_pk_bf16_f32 v139, v106, v107
	global_store_dwordx4 v218, v[136:139], s[14:15]
	v_add_u32_e32 v219, 0xc000, v217
	v_pk_mul_f32 v[140:141], v[68:69], v[242:243]
	v_pk_mul_f32 v[142:143], v[70:71], v[242:243]
	v_pk_mul_f32 v[144:145], v[64:65], v[242:243]
	v_pk_mul_f32 v[146:147], v[66:67], v[242:243]
	v_exp_f32_e32 v140, v140
	v_exp_f32_e32 v141, v141
	v_exp_f32_e32 v142, v142
	v_exp_f32_e32 v143, v143
	v_exp_f32_e32 v144, v144
	v_exp_f32_e32 v145, v145
	v_exp_f32_e32 v146, v146
	v_exp_f32_e32 v147, v147
	v_pk_add_f32 v[140:141], v[140:141], 1.0 op_sel_hi:[1,0]
	v_pk_add_f32 v[142:143], v[142:143], 1.0 op_sel_hi:[1,0]
	v_pk_add_f32 v[144:145], v[144:145], 1.0 op_sel_hi:[1,0]
	v_pk_add_f32 v[146:147], v[146:147], 1.0 op_sel_hi:[1,0]
	v_rcp_f32_e32 v140, v140
	v_rcp_f32_e32 v141, v141
	v_rcp_f32_e32 v142, v142
	v_rcp_f32_e32 v143, v143
	v_rcp_f32_e32 v144, v144
	v_rcp_f32_e32 v145, v145
	v_rcp_f32_e32 v146, v146
	v_rcp_f32_e32 v147, v147
	v_pk_mul_f32 v[100:101], v[100:101], v[140:141]
	v_pk_mul_f32 v[102:103], v[102:103], v[142:143]
	v_pk_mul_f32 v[96:97], v[96:97], v[144:145]
; __device__ __forceinline__ u32x4 pack8(f32x4 a, f32x4 b) { u32x4 w; w.x = pk2(a[0], a[1]); w.y = pk2(a[2], a[3]); w.z = pk2(b[0], b[1]); w.w = pk2(b[2], b[3]); return w; }
; __device__ __forceinline__ f32x4 sigm4(f32x4 v) { return (f32x4){sigm(v[0]), sigm(v[1]), sigm(v[2]), sigm(v[3])}; }
; #define FOR_ROWS _Pragma("unroll") for (int ai = 0; ai < 2; ++ai) _Pragma("unroll") for (int m = 0; m < 4; ++m)
; __device__ __forceinline__ void epilogue(const int kind, CParams& p, const f32x4 (&acc)[2][2][4][2], const Unit& u, const int wr, const int wc, const int fr_in, const int fq_in) {
;     ...
;     case E_G1: {
;         if (u.pn < 4) {
;             FOR_ROWS { ROWDEF
;                 const f32x4 a0 = acc[ai][0][m][0], a1 = acc[ai][0][m][1], b0 = sigm4(acc[ai][1][m][0]), b1 = sigm4(acc[ai][1][m][1]);
;                 *(u32x4*)(p.u + row * DCV + u.pn * 128 + cw) = pack8(a0 * b0, a1 * b1); }
	v_pk_mul_f32 v[98:99], v[98:99], v[146:147]
	v_cvt_pk_bf16_f32 v148, v100, v101
	v_cvt_pk_bf16_f32 v149, v102, v103
	v_cvt_pk_bf16_f32 v150, v96, v97
	v_cvt_pk_bf16_f32 v151, v98, v99
	global_store_dwordx4 v219, v[148:151], s[14:15]
	v_add_u32_e32 v218, 0x20000, v217
	v_pk_mul_f32 v[128:129], v[28:29], v[242:243]
	v_pk_mul_f32 v[130:131], v[30:31], v[242:243]
	v_pk_mul_f32 v[132:133], v[24:25], v[242:243]
	v_pk_mul_f32 v[134:135], v[26:27], v[242:243]
	v_exp_f32_e32 v128, v128
	v_exp_f32_e32 v129, v129
	v_exp_f32_e32 v130, v130
	v_exp_f32_e32 v131, v131
	v_exp_f32_e32 v132, v132
	v_exp_f32_e32 v133, v133
	v_exp_f32_e32 v134, v134
	v_exp_f32_e32 v135, v135
	v_pk_add_f32 v[128:129], v[128:129], 1.0 op_sel_hi:[1,0]
	v_pk_add_f32 v[130:131], v[130:131], 1.0 op_sel_hi:[1,0]
	v_pk_add_f32 v[132:133], v[132:133], 1.0 op_sel_hi:[1,0]
	v_pk_add_f32 v[134:135], v[134:135], 1.0 op_sel_hi:[1,0]
	v_rcp_f32_e32 v128, v128
	v_rcp_f32_e32 v129, v129
	v_rcp_f32_e32 v130, v130
	v_rcp_f32_e32 v131, v131
	v_rcp_f32_e32 v132, v132
	v_rcp_f32_e32 v133, v133
	v_rcp_f32_e32 v134, v134
	v_rcp_f32_e32 v135, v135
	v_pk_mul_f32 v[60:61], v[60:61], v[128:129]
	v_pk_mul_f32 v[62:63], v[62:63], v[130:131]
	v_pk_mul_f32 v[56:57], v[56:57], v[132:133]
	v_pk_mul_f32 v[58:59], v[58:59], v[134:135]
	v_cvt_pk_bf16_f32 v136, v60, v61
	v_cvt_pk_bf16_f32 v137, v62, v63
	v_cvt_pk_bf16_f32 v138, v56, v57
	v_cvt_pk_bf16_f32 v139, v58, v59
	global_store_dwordx4 v218, v[136:139], s[14:15]
	v_add_u32_e32 v219, 0x24000, v217
	v_pk_mul_f32 v[140:141], v[20:21], v[242:243]
	v_pk_mul_f32 v[142:143], v[22:23], v[242:243]
	v_pk_mul_f32 v[144:145], v[16:17], v[242:243]
	v_pk_mul_f32 v[146:147], v[18:19], v[242:243]
	v_exp_f32_e32 v140, v140
	v_exp_f32_e32 v141, v141
	v_exp_f32_e32 v142, v142
	v_exp_f32_e32 v143, v143
	v_exp_f32_e32 v144, v144
	v_exp_f32_e32 v145, v145
	v_exp_f32_e32 v146, v146
	v_exp_f32_e32 v147, v147
	v_pk_add_f32 v[140:141], v[140:141], 1.0 op_sel_hi:[1,0]
	v_pk_add_f32 v[142:143], v[142:143], 1.0 op_sel_hi:[1,0]
	v_pk_add_f32 v[144:145], v[144:145], 1.0 op_sel_hi:[1,0]
	v_pk_add_f32 v[146:147], v[146:147], 1.0 op_sel_hi:[1,0]
	v_rcp_f32_e32 v140, v140
	v_rcp_f32_e32 v141, v141
	v_rcp_f32_e32 v142, v142
	v_rcp_f32_e32 v143, v143
	v_rcp_f32_e32 v144, v144
	v_rcp_f32_e32 v145, v145
	v_rcp_f32_e32 v146, v146
	v_rcp_f32_e32 v147, v147
	v_pk_mul_f32 v[52:53], v[52:53], v[140:141]
	v_pk_mul_f32 v[54:55], v[54:55], v[142:143]
	v_pk_mul_f32 v[48:49], v[48:49], v[144:145]
	v_pk_mul_f32 v[50:51], v[50:51], v[146:147]
	v_cvt_pk_bf16_f32 v148, v52, v53
	v_cvt_pk_bf16_f32 v149, v54, v55
	v_cvt_pk_bf16_f32 v150, v48, v49
	v_cvt_pk_bf16_f32 v151, v50, v51
	global_store_dwordx4 v219, v[148:151], s[14:15]
	v_add_u32_e32 v218, 0x28000, v217
	v_pk_mul_f32 v[128:129], v[12:13], v[242:243]
	v_pk_mul_f32 v[130:131], v[14:15], v[242:243]
	v_pk_mul_f32 v[132:133], v[8:9], v[242:243]
	v_pk_mul_f32 v[134:135], v[10:11], v[242:243]
	v_exp_f32_e32 v128, v128
	v_exp_f32_e32 v129, v129
	v_exp_f32_e32 v130, v130
	v_exp_f32_e32 v131, v131
	v_exp_f32_e32 v132, v132
	v_exp_f32_e32 v133, v133
	v_exp_f32_e32 v134, v134
	v_exp_f32_e32 v135, v135
	v_pk_add_f32 v[128:129], v[128:129], 1.0 op_sel_hi:[1,0]
	v_pk_add_f32 v[130:131], v[130:131], 1.0 op_sel_hi:[1,0]
	v_pk_add_f32 v[132:133], v[132:133], 1.0 op_sel_hi:[1,0]
	v_pk_add_f32 v[134:135], v[134:135], 1.0 op_sel_hi:[1,0]
	v_rcp_f32_e32 v128, v128
	v_rcp_f32_e32 v129, v129
	v_rcp_f32_e32 v130, v130
	v_rcp_f32_e32 v131, v131
	v_rcp_f32_e32 v132, v132
	v_rcp_f32_e32 v133, v133
	v_rcp_f32_e32 v134, v134
	v_rcp_f32_e32 v135, v135
	v_pk_mul_f32 v[44:45], v[44:45], v[128:129]
	v_pk_mul_f32 v[46:47], v[46:47], v[130:131]
	v_pk_mul_f32 v[40:41], v[40:41], v[132:133]
	v_pk_mul_f32 v[42:43], v[42:43], v[134:135]
	v_cvt_pk_bf16_f32 v136, v44, v45
	v_cvt_pk_bf16_f32 v137, v46, v47
	v_cvt_pk_bf16_f32 v138, v40, v41
	v_cvt_pk_bf16_f32 v139, v42, v43
	global_store_dwordx4 v218, v[136:139], s[14:15]
	v_add_u32_e32 v219, 0x2c000, v217
	v_pk_mul_f32 v[140:141], v[4:5], v[242:243]
	v_pk_mul_f32 v[142:143], v[6:7], v[242:243]
	v_pk_mul_f32 v[144:145], v[0:1], v[242:243]
	v_pk_mul_f32 v[146:147], v[2:3], v[242:243]
	v_exp_f32_e32 v140, v140
	v_exp_f32_e32 v141, v141
	v_exp_f32_e32 v142, v142
	v_exp_f32_e32 v143, v143
	v_exp_f32_e32 v144, v144
	v_exp_f32_e32 v145, v145
	v_exp_f32_e32 v146, v146
	v_exp_f32_e32 v147, v147
	v_pk_add_f32 v[140:141], v[140:141], 1.0 op_sel_hi:[1,0]
	v_pk_add_f32 v[142:143], v[142:143], 1.0 op_sel_hi:[1,0]
	v_pk_add_f32 v[144:145], v[144:145], 1.0 op_sel_hi:[1,0]
	v_pk_add_f32 v[146:147], v[146:147], 1.0 op_sel_hi:[1,0]
	v_rcp_f32_e32 v140, v140
	v_rcp_f32_e32 v141, v141
	v_rcp_f32_e32 v142, v142
	v_rcp_f32_e32 v143, v143
	v_rcp_f32_e32 v144, v144
	v_rcp_f32_e32 v145, v145
	v_rcp_f32_e32 v146, v146
	v_rcp_f32_e32 v147, v147
	v_pk_mul_f32 v[36:37], v[36:37], v[140:141]
	v_pk_mul_f32 v[38:39], v[38:39], v[142:143]
	v_pk_mul_f32 v[32:33], v[32:33], v[144:145]
	v_pk_mul_f32 v[34:35], v[34:35], v[146:147]
	v_cvt_pk_bf16_f32 v148, v36, v37
	v_cvt_pk_bf16_f32 v149, v38, v39
	v_cvt_pk_bf16_f32 v150, v32, v33
	v_cvt_pk_bf16_f32 v151, v34, v35
	global_store_dwordx4 v219, v[148:151], s[14:15]
	s_nop 1
	s_branch .LBB0_911
